# attention: last P.V block's four MFMAs issued behind the first per-tile barrier, interleaved with the three LDS-DMA issues; its V reads waited in front of the barrier
# speedup vs baseline: 1.0070x; 1.0070x over previous
.LBB0_1031:
	s_lshl_b32 s0, s75, 13
	s_add_i32 s77, s0, 0
	s_setprio 1
	v_add_u32_e32 v112, s77, v189
	v_add_u32_e32 v68, v112, v191
	ds_read_b128 v[64:67], v68 offset:49152
	ds_read_b128 v[68:71], v68 offset:53248
	v_add_u32_e32 v113, v112, v192
	ds_read_b128 v[220:223], v113 offset:49152
	ds_read_b128 v[224:227], v113 offset:53248
	v_add_u32_e32 v113, v112, v193
	s_waitcnt lgkmcnt(0)
	v_mfma_f32_32x32x16_bf16 v[80:95], v[64:67], v[108:111], 0
	v_add_u32_e32 v112, v112, v194
	v_mfma_f32_32x32x16_bf16 v[64:79], v[68:71], v[108:111], 0
	v_mfma_f32_32x32x16_bf16 v[80:95], v[220:223], v[104:107], v[80:95]
	v_mfma_f32_32x32x16_bf16 v[64:79], v[224:227], v[104:107], v[64:79]
	ds_read_b128 v[220:223], v113 offset:49152
	ds_read_b128 v[224:227], v113 offset:53248
	s_waitcnt lgkmcnt(0)
	v_mfma_f32_32x32x16_bf16 v[80:95], v[220:223], v[100:103], v[80:95]
	v_mfma_f32_32x32x16_bf16 v[64:79], v[224:227], v[100:103], v[64:79]
	ds_read_b128 v[220:223], v112 offset:49152
	ds_read_b128 v[224:227], v112 offset:53248
	s_waitcnt lgkmcnt(0)
	v_mfma_f32_32x32x16_bf16 v[80:95], v[220:223], v[96:99], v[80:95]
	v_mfma_f32_32x32x16_bf16 v[64:79], v[224:227], v[96:99], v[64:79]
	s_setprio 0
	v_exp_f32_e32 v174, v174
	v_exp_f32_e32 v175, v175
	v_add_f32_e32 v112, v115, v174
	v_add_f32_e32 v113, v124, v175
	v_exp_f32_e32 v172, v172
	v_add_f32_e32 v112, v112, v125
	v_add_f32_e32 v113, v113, v126
	v_exp_f32_e32 v173, v173
	v_add_f32_e32 v112, v112, v172
	v_add_f32_e32 v113, v113, v173
	v_exp_f32_e32 v170, v170
	v_add_f32_e32 v112, v112, v127
	v_add_f32_e32 v113, v113, v176
	v_exp_f32_e32 v171, v171
	v_add_f32_e32 v112, v112, v170
	v_add_f32_e32 v113, v113, v171
	v_exp_f32_e32 v168, v168
	v_add_f32_e32 v112, v112, v177
	v_add_f32_e32 v113, v113, v178
	v_exp_f32_e32 v169, v169
	v_add_f32_e32 v112, v112, v168
	v_add_f32_e32 v113, v113, v169
	v_exp_f32_e32 v166, v166
	v_add_f32_e32 v112, v112, v116
	v_add_f32_e32 v113, v113, v117
	v_exp_f32_e32 v167, v167
	v_add_f32_e32 v112, v112, v166
	v_add_f32_e32 v113, v113, v167
	v_exp_f32_e32 v164, v164
	v_add_f32_e32 v112, v112, v118
	v_add_f32_e32 v113, v113, v119
	v_exp_f32_e32 v165, v165
	v_add_f32_e32 v112, v112, v164
	v_add_f32_e32 v113, v113, v165
	v_exp_f32_e32 v162, v162
	v_add_f32_e32 v112, v112, v120
	v_add_f32_e32 v113, v113, v121
	v_exp_f32_e32 v163, v163
	v_exp_f32_e32 v160, v160
	v_exp_f32_e32 v161, v161
	v_add_f32_e32 v112, v112, v162
	v_add_f32_e32 v113, v113, v163
	s_nop 0
	v_add_f32_e32 v112, v112, v122
	v_add_f32_e32 v113, v113, v123
	s_nop 0
	v_add_f32_e32 v112, v112, v160
	v_add_f32_e32 v113, v113, v161
	s_nop 0
	v_add_f32_e32 v219, v112, v113
	v_cvt_pk_bf16_f32 v112, v115, v124
	v_cvt_pk_bf16_f32 v113, v125, v126
	v_cvt_pk_bf16_f32 v114, v127, v176
	v_cvt_pk_bf16_f32 v115, v177, v178
	v_cvt_pk_bf16_f32 v116, v116, v117
	s_nop 0
	v_mov_b32_e32 v220, v219
	s_nop 1
	v_permlane32_swap_b32_e32 v219, v220
	v_cvt_pk_bf16_f32 v117, v118, v119
	v_cvt_pk_bf16_f32 v118, v120, v121
	v_cvt_pk_bf16_f32 v119, v122, v123
	v_cvt_pk_bf16_f32 v120, v174, v175
	v_cvt_pk_bf16_f32 v121, v172, v173
	v_cvt_pk_bf16_f32 v122, v170, v171
	v_cvt_pk_bf16_f32 v123, v168, v169
	v_cvt_pk_bf16_f32 v124, v166, v167
	v_cvt_pk_bf16_f32 v125, v164, v165
	v_cvt_pk_bf16_f32 v126, v162, v163
	v_cvt_pk_bf16_f32 v127, v160, v161
	v_permlane32_swap_b32_e32 v112, v114
	v_permlane32_swap_b32_e32 v113, v115
	v_permlane32_swap_b32_e32 v116, v118
	v_permlane32_swap_b32_e32 v117, v119
	v_permlane32_swap_b32_e32 v120, v122
	v_permlane32_swap_b32_e32 v121, v123
	v_permlane32_swap_b32_e32 v124, v126
	v_permlane32_swap_b32_e32 v125, v127
	s_lshl_b32 s0, s76, 14
	v_add_u32_e32 v176, s0, v187
	ds_read_b64_tr_b16 v[160:161], v176 offset:0
	ds_read_b64_tr_b16 v[162:163], v176 offset:0x800
	ds_read_b64_tr_b16 v[164:165], v176 offset:0x1000
	ds_read_b64_tr_b16 v[166:167], v176 offset:0x1800
	ds_read_b64_tr_b16 v[168:169], v176 offset:0x2000
	ds_read_b64_tr_b16 v[170:171], v176 offset:0x2800
	ds_read_b64_tr_b16 v[172:173], v176 offset:0x3000
	ds_read_b64_tr_b16 v[174:175], v176 offset:0x3800
	s_setprio 1
	s_waitcnt lgkmcnt(6)
	v_mfma_f32_32x32x16_bf16 v[48:63], v[112:115], v[160:163], v[48:63]
	s_waitcnt lgkmcnt(4)
	v_mfma_f32_32x32x16_bf16 v[48:63], v[116:119], v[164:167], v[48:63]
	s_waitcnt lgkmcnt(2)
	v_mfma_f32_32x32x16_bf16 v[48:63], v[120:123], v[168:171], v[48:63]
	s_waitcnt lgkmcnt(0)
	v_mfma_f32_32x32x16_bf16 v[48:63], v[124:127], v[172:175], v[48:63]
	s_setprio 0
	v_max3_f32 v160, v80, v81, v82
	v_max3_f32 v161, v64, v65, v66
	v_max_f32_e32 v162, v79, v79
	v_max3_f32 v160, v160, v83, v84
	v_max3_f32 v161, v161, v67, v68
	v_max_f32_e32 v163, v95, v95
	v_max3_f32 v160, v160, v85, v86
	v_max3_f32 v161, v161, v69, v70
	v_max_f32_e32 v162, v163, v162
	v_max3_f32 v160, v160, v87, v88
	v_max3_f32 v161, v161, v71, v72
	s_nop 0
	v_max3_f32 v160, v160, v89, v90
	v_max3_f32 v161, v161, v73, v74
	s_nop 0
	v_max3_f32 v160, v160, v91, v92
	v_max3_f32 v161, v161, v75, v76
	s_nop 0
	v_max3_f32 v160, v160, v93, v94
	v_max3_f32 v161, v161, v77, v78
	s_nop 0
	v_max3_f32 v160, v160, v161, v162
	s_nop 0
	v_mov_b32_e32 v161, v160
	s_nop 1
	v_permlane32_swap_b32_e32 v160, v161
	v_max_f32_e32 v161, v161, v161
	v_max_f32_e32 v160, v160, v160
	v_max_f32_e32 v177, v160, v161
	ds_read_b64_tr_b16 v[160:161], v176 offset:0x200
	ds_read_b64_tr_b16 v[162:163], v176 offset:0xa00
	ds_read_b64_tr_b16 v[164:165], v176 offset:0x1200
	ds_read_b64_tr_b16 v[166:167], v176 offset:0x1a00
	ds_read_b64_tr_b16 v[168:169], v176 offset:0x2200
	ds_read_b64_tr_b16 v[170:171], v176 offset:0x2a00
	ds_read_b64_tr_b16 v[172:173], v176 offset:0x3200
	ds_read_b64_tr_b16 v[174:175], v176 offset:0x3a00
	s_setprio 1
	s_waitcnt lgkmcnt(6)
	v_mfma_f32_32x32x16_bf16 v[32:47], v[112:115], v[160:163], v[32:47]
	s_waitcnt lgkmcnt(4)
	v_mfma_f32_32x32x16_bf16 v[32:47], v[116:119], v[164:167], v[32:47]
	s_waitcnt lgkmcnt(2)
	v_mfma_f32_32x32x16_bf16 v[32:47], v[120:123], v[168:171], v[32:47]
	s_waitcnt lgkmcnt(0)
	v_mfma_f32_32x32x16_bf16 v[32:47], v[124:127], v[172:175], v[32:47]
	s_setprio 0
	v_sub_f32_e32 v160, v177, v218
	v_cmp_ge_f32_e32 vcc, s71, v160
	v_max_f32_e32 v160, v218, v218
	v_max_f32_e32 v160, v160, v177
	v_sub_f32_e32 v161, v218, v160
	v_mul_f32_e32 v161, 0x3e38aa3b, v161
	v_exp_f32_e32 v161, v161
	s_cmp_eq_u64 vcc, exec
	s_cselect_b64 vcc, -1, 0
	v_cndmask_b32_e32 v222, v160, v218, vcc
	v_cndmask_b32_e64 v221, v161, 1.0, vcc
	v_mul_f32_e32 v175, 0xbe38aa3b, v222
	v_fma_f32 v80, v80, v197, v175
	v_fma_f32 v81, v81, v197, v175
	v_fma_f32 v82, v82, v197, v175
	v_fma_f32 v83, v83, v197, v175
	v_fma_f32 v84, v84, v197, v175
	v_fma_f32 v85, v85, v197, v175
	v_fma_f32 v86, v86, v197, v175
	v_fma_f32 v87, v87, v197, v175
	v_fma_f32 v88, v88, v197, v175
	v_fma_f32 v89, v89, v197, v175
	v_fma_f32 v90, v90, v197, v175
	v_fma_f32 v91, v91, v197, v175
	v_fma_f32 v92, v92, v197, v175
	v_fma_f32 v93, v93, v197, v175
	v_fma_f32 v94, v94, v197, v175
	v_fma_f32 v95, v95, v197, v175
	v_fma_f32 v160, v64, v197, v175
	v_fma_f32 v161, v65, v197, v175
	v_fma_f32 v162, v66, v197, v175
	v_fma_f32 v163, v67, v197, v175
	v_fma_f32 v164, v68, v197, v175
	v_fma_f32 v165, v69, v197, v175
	v_fma_f32 v166, v70, v197, v175
	v_fma_f32 v167, v71, v197, v175
	v_fma_f32 v168, v72, v197, v175
	v_fma_f32 v169, v73, v197, v175
	v_fma_f32 v170, v74, v197, v175
	v_fma_f32 v171, v75, v197, v175
	v_fma_f32 v172, v76, v197, v175
	v_fma_f32 v173, v77, v197, v175
	v_fma_f32 v174, v78, v197, v175
	v_fma_f32 v175, v79, v197, v175
	ds_read_b64_tr_b16 v[64:65], v176 offset:0x400
	ds_read_b64_tr_b16 v[66:67], v176 offset:0xc00
	ds_read_b64_tr_b16 v[68:69], v176 offset:0x1400
	ds_read_b64_tr_b16 v[70:71], v176 offset:0x1c00
	ds_read_b64_tr_b16 v[72:73], v176 offset:0x2400
	ds_read_b64_tr_b16 v[74:75], v176 offset:0x2c00
	ds_read_b64_tr_b16 v[76:77], v176 offset:0x3400
	ds_read_b64_tr_b16 v[78:79], v176 offset:0x3c00
	s_setprio 1
	s_waitcnt lgkmcnt(6)
	v_mfma_f32_32x32x16_bf16 v[16:31], v[112:115], v[64:67], v[16:31]
	s_waitcnt lgkmcnt(4)
	v_mfma_f32_32x32x16_bf16 v[16:31], v[116:119], v[68:71], v[16:31]
	s_waitcnt lgkmcnt(2)
	v_mfma_f32_32x32x16_bf16 v[16:31], v[120:123], v[72:75], v[16:31]
	s_waitcnt lgkmcnt(0)
	v_mfma_f32_32x32x16_bf16 v[16:31], v[124:127], v[76:79], v[16:31]
	s_setprio 0
	ds_read_b64_tr_b16 v[64:65], v176 offset:0x600
	ds_read_b64_tr_b16 v[66:67], v176 offset:0xe00
	ds_read_b64_tr_b16 v[68:69], v176 offset:0x1600
	ds_read_b64_tr_b16 v[70:71], v176 offset:0x1e00
	ds_read_b64_tr_b16 v[72:73], v176 offset:0x2600
	ds_read_b64_tr_b16 v[74:75], v176 offset:0x2e00
	ds_read_b64_tr_b16 v[76:77], v176 offset:0x3600
	ds_read_b64_tr_b16 v[78:79], v176 offset:0x3e00
	s_setprio 0
	s_lshl_b32 s1, s76, 13
	v_lshl_add_u64 v[176:177], s[46:47], 0, v[154:155]
	s_mov_b64 s[48:49], 0x14210800
	s_add_i32 s1, s51, s1
	s_waitcnt vmcnt(0) lgkmcnt(0)
	s_barrier
	s_setprio 1
	v_mfma_f32_32x32x16_bf16 v[0:15], v[112:115], v[64:67], v[0:15]
	v_lshl_add_u64 v[226:227], v[176:177], 0, s[48:49]
	s_add_i32 m0, s1, 0xc000
	v_lshl_add_u64 v[178:179], s[46:47], 0, v[156:157]
	s_add_i32 s0, s51, s0
	global_load_lds_dwordx4 v[226:227], off
	v_mfma_f32_32x32x16_bf16 v[0:15], v[116:119], v[68:71], v[0:15]
	v_lshl_add_u64 v[226:227], v[178:179], 0, s[10:11]
	s_mov_b32 m0, s0
	v_lshl_add_u64 v[180:181], s[46:47], 0, v[158:159]
	global_load_lds_dwordx4 v[226:227], off
	v_mfma_f32_32x32x16_bf16 v[0:15], v[120:123], v[72:75], v[0:15]
	v_lshl_add_u64 v[226:227], v[180:181], 0, s[10:11]
	s_add_i32 m0, s0, 0x2000
	v_cmp_gt_f32_e32 vcc, 1.0, v221
	global_load_lds_dwordx4 v[226:227], off
	v_mfma_f32_32x32x16_bf16 v[0:15], v[124:127], v[76:79], v[0:15]
	s_setprio 0
	s_cbranch_vccz .LBB0_1035
	s_and_saveexec_b64 s[0:1], s[4:5]
	ds_write_b32 v215, v221 offset:128
	s_or_b64 exec, exec, s[0:1]
	s_waitcnt lgkmcnt(0)
	v_add_u32_e32 v76, s50, v188
	ds_read_b128 v[64:67], v76 offset:224
	ds_read_b128 v[68:71], v76 offset:192
	ds_read_b128 v[72:75], v76 offset:160
	ds_read_b128 v[76:79], v76 offset:128
	s_waitcnt lgkmcnt(0)
	v_pk_mul_f32 v[60:61], v[60:61], v[64:65]
	v_pk_mul_f32 v[56:57], v[56:57], v[68:69]
	v_pk_mul_f32 v[52:53], v[52:53], v[72:73]
	v_pk_mul_f32 v[62:63], v[62:63], v[66:67]
	v_pk_mul_f32 v[58:59], v[58:59], v[70:71]
	v_pk_mul_f32 v[54:55], v[54:55], v[74:75]
	v_pk_mul_f32 v[50:51], v[50:51], v[78:79]
	v_pk_mul_f32 v[48:49], v[48:49], v[76:77]
	v_pk_mul_f32 v[44:45], v[44:45], v[64:65]
	v_pk_mul_f32 v[40:41], v[40:41], v[68:69]
	v_pk_mul_f32 v[36:37], v[36:37], v[72:73]
	v_pk_mul_f32 v[46:47], v[46:47], v[66:67]
	v_pk_mul_f32 v[42:43], v[42:43], v[70:71]
	v_pk_mul_f32 v[38:39], v[38:39], v[74:75]
	v_pk_mul_f32 v[34:35], v[34:35], v[78:79]
	v_pk_mul_f32 v[32:33], v[32:33], v[76:77]
	v_pk_mul_f32 v[28:29], v[28:29], v[64:65]
	v_pk_mul_f32 v[24:25], v[24:25], v[68:69]
	v_pk_mul_f32 v[20:21], v[20:21], v[72:73]
	v_pk_mul_f32 v[30:31], v[30:31], v[66:67]
	v_pk_mul_f32 v[26:27], v[26:27], v[70:71]
	v_pk_mul_f32 v[22:23], v[22:23], v[74:75]
	v_pk_mul_f32 v[18:19], v[18:19], v[78:79]
	v_pk_mul_f32 v[16:17], v[16:17], v[76:77]
	v_pk_mul_f32 v[12:13], v[12:13], v[64:65]
	v_pk_mul_f32 v[8:9], v[8:9], v[68:69]
	v_pk_mul_f32 v[4:5], v[4:5], v[72:73]
	v_pk_mul_f32 v[14:15], v[14:15], v[66:67]
	v_pk_mul_f32 v[10:11], v[10:11], v[70:71]
	v_pk_mul_f32 v[6:7], v[6:7], v[74:75]
	v_pk_mul_f32 v[2:3], v[2:3], v[78:79]
	v_pk_mul_f32 v[0:1], v[0:1], v[76:77]

.LBB0_1050:
	s_lshl_b32 s0, s76, 13
	s_add_i32 s40, s0, 0
	s_setprio 1
	v_add_u32_e32 v112, s40, v189
	v_add_u32_e32 v68, v112, v191
	ds_read_b128 v[64:67], v68 offset:49152
	ds_read_b128 v[68:71], v68 offset:53248
	v_add_u32_e32 v113, v112, v192
	ds_read_b128 v[228:231], v113 offset:49152
	ds_read_b128 v[232:235], v113 offset:53248
	v_add_u32_e32 v113, v112, v193
	s_waitcnt lgkmcnt(0)
	v_mfma_f32_32x32x16_bf16 v[80:95], v[64:67], v[108:111], 0
	v_add_u32_e32 v112, v112, v194
	v_mfma_f32_32x32x16_bf16 v[64:79], v[68:71], v[108:111], 0
	v_mfma_f32_32x32x16_bf16 v[80:95], v[228:231], v[104:107], v[80:95]
	v_mfma_f32_32x32x16_bf16 v[64:79], v[232:235], v[104:107], v[64:79]
	ds_read_b128 v[228:231], v113 offset:49152
	ds_read_b128 v[232:235], v113 offset:53248
	s_waitcnt lgkmcnt(0)
	v_mfma_f32_32x32x16_bf16 v[80:95], v[228:231], v[100:103], v[80:95]
	v_mfma_f32_32x32x16_bf16 v[64:79], v[232:235], v[100:103], v[64:79]
	ds_read_b128 v[228:231], v112 offset:49152
	ds_read_b128 v[232:235], v112 offset:53248
	s_waitcnt lgkmcnt(0)
	v_mfma_f32_32x32x16_bf16 v[80:95], v[228:231], v[96:99], v[80:95]
	v_mfma_f32_32x32x16_bf16 v[64:79], v[232:235], v[96:99], v[64:79]
	s_setprio 0
	v_exp_f32_e32 v163, v180
	v_exp_f32_e32 v164, v181
	v_add_f32_e32 v112, v115, v163
	v_add_f32_e32 v113, v124, v164
	v_exp_f32_e32 v165, v178
	v_add_f32_e32 v112, v112, v125
	v_add_f32_e32 v113, v113, v126
	v_exp_f32_e32 v178, v179
	v_add_f32_e32 v112, v112, v165
	v_add_f32_e32 v113, v113, v178
	v_exp_f32_e32 v176, v176
	v_add_f32_e32 v112, v112, v127
	v_add_f32_e32 v113, v113, v160
	v_exp_f32_e32 v177, v177
	v_add_f32_e32 v112, v112, v176
	v_add_f32_e32 v113, v113, v177
	v_exp_f32_e32 v174, v174
	v_add_f32_e32 v112, v112, v161
	v_add_f32_e32 v113, v113, v162
	v_exp_f32_e32 v175, v175
	v_add_f32_e32 v112, v112, v174
	v_add_f32_e32 v113, v113, v175
	v_exp_f32_e32 v172, v172
	v_add_f32_e32 v112, v112, v116
	v_add_f32_e32 v113, v113, v117
	v_exp_f32_e32 v173, v173
	v_add_f32_e32 v112, v112, v172
	v_add_f32_e32 v113, v113, v173
	v_exp_f32_e32 v170, v170
	v_add_f32_e32 v112, v112, v118
	v_add_f32_e32 v113, v113, v119
	v_exp_f32_e32 v171, v171
	v_add_f32_e32 v112, v112, v170
	v_add_f32_e32 v113, v113, v171
	v_exp_f32_e32 v168, v168
	v_add_f32_e32 v112, v112, v120
	v_add_f32_e32 v113, v113, v121
	v_exp_f32_e32 v169, v169
	v_exp_f32_e32 v166, v166
	v_exp_f32_e32 v167, v167
	v_add_f32_e32 v112, v112, v168
	v_add_f32_e32 v113, v113, v169
	s_nop 0
	v_add_f32_e32 v112, v112, v122
	v_add_f32_e32 v113, v113, v123
	s_nop 0
	v_add_f32_e32 v112, v112, v166
	v_add_f32_e32 v113, v113, v167
	s_nop 0
	v_add_f32_e32 v225, v112, v113
	v_cvt_pk_bf16_f32 v112, v115, v124
	v_cvt_pk_bf16_f32 v113, v125, v126
	v_cvt_pk_bf16_f32 v114, v127, v160
	v_cvt_pk_bf16_f32 v115, v161, v162
	v_cvt_pk_bf16_f32 v116, v116, v117
	s_nop 0
	v_mov_b32_e32 v226, v225
	s_nop 1
	v_permlane32_swap_b32_e32 v225, v226
	v_cvt_pk_bf16_f32 v117, v118, v119
	v_cvt_pk_bf16_f32 v118, v120, v121
	v_cvt_pk_bf16_f32 v119, v122, v123
	v_cvt_pk_bf16_f32 v120, v163, v164
	v_cvt_pk_bf16_f32 v121, v165, v178
	v_cvt_pk_bf16_f32 v122, v176, v177
	v_cvt_pk_bf16_f32 v123, v174, v175
	v_cvt_pk_bf16_f32 v124, v172, v173
	v_cvt_pk_bf16_f32 v125, v170, v171
	v_cvt_pk_bf16_f32 v126, v168, v169
	v_cvt_pk_bf16_f32 v127, v166, v167
	v_permlane32_swap_b32_e32 v112, v114
	v_permlane32_swap_b32_e32 v113, v115
	v_permlane32_swap_b32_e32 v116, v118
	v_permlane32_swap_b32_e32 v117, v119
	v_permlane32_swap_b32_e32 v120, v122
	v_permlane32_swap_b32_e32 v121, v123
	v_permlane32_swap_b32_e32 v124, v126
	v_permlane32_swap_b32_e32 v125, v127
	s_lshl_b32 s0, s36, 14
	v_add_u32_e32 v230, s0, v187
	ds_read_b64_tr_b16 v[160:161], v230 offset:0
	ds_read_b64_tr_b16 v[162:163], v230 offset:0x800
	ds_read_b64_tr_b16 v[164:165], v230 offset:0x1000
	ds_read_b64_tr_b16 v[166:167], v230 offset:0x1800
	ds_read_b64_tr_b16 v[168:169], v230 offset:0x2000
	ds_read_b64_tr_b16 v[170:171], v230 offset:0x2800
	ds_read_b64_tr_b16 v[172:173], v230 offset:0x3000
	ds_read_b64_tr_b16 v[174:175], v230 offset:0x3800
	s_setprio 1
	s_waitcnt lgkmcnt(6)
	v_mfma_f32_32x32x16_bf16 v[48:63], v[112:115], v[160:163], v[48:63]
	s_waitcnt lgkmcnt(4)
	v_mfma_f32_32x32x16_bf16 v[48:63], v[116:119], v[164:167], v[48:63]
	s_waitcnt lgkmcnt(2)
	v_mfma_f32_32x32x16_bf16 v[48:63], v[120:123], v[168:171], v[48:63]
	s_waitcnt lgkmcnt(0)
	v_mfma_f32_32x32x16_bf16 v[48:63], v[124:127], v[172:175], v[48:63]
	s_setprio 0
	v_max3_f32 v160, v80, v81, v82
	v_max3_f32 v161, v64, v65, v66
	v_max_f32_e32 v162, v79, v79
	v_max3_f32 v160, v160, v83, v84
	v_max3_f32 v161, v161, v67, v68
	v_max_f32_e32 v163, v95, v95
	v_max3_f32 v160, v160, v85, v86
	v_max3_f32 v161, v161, v69, v70
	v_max_f32_e32 v162, v163, v162
	v_max3_f32 v160, v160, v87, v88
	v_max3_f32 v161, v161, v71, v72
	s_nop 0
	v_max3_f32 v160, v160, v89, v90
	v_max3_f32 v161, v161, v73, v74
	s_nop 0
	v_max3_f32 v160, v160, v91, v92
	v_max3_f32 v161, v161, v75, v76
	s_nop 0
	v_max3_f32 v160, v160, v93, v94
	v_max3_f32 v161, v161, v77, v78
	s_nop 0
	v_max3_f32 v160, v160, v161, v162
	s_nop 0
	v_mov_b32_e32 v161, v160
	s_nop 1
	v_permlane32_swap_b32_e32 v160, v161
	v_max_f32_e32 v161, v161, v161
	v_max_f32_e32 v160, v160, v160
	v_max_f32_e32 v176, v160, v161
	ds_read_b64_tr_b16 v[160:161], v230 offset:0x200
	ds_read_b64_tr_b16 v[162:163], v230 offset:0xa00
	ds_read_b64_tr_b16 v[164:165], v230 offset:0x1200
	ds_read_b64_tr_b16 v[166:167], v230 offset:0x1a00
	ds_read_b64_tr_b16 v[168:169], v230 offset:0x2200
	ds_read_b64_tr_b16 v[170:171], v230 offset:0x2a00
	ds_read_b64_tr_b16 v[172:173], v230 offset:0x3200
	ds_read_b64_tr_b16 v[174:175], v230 offset:0x3a00
	s_setprio 1
	s_waitcnt lgkmcnt(6)
	v_mfma_f32_32x32x16_bf16 v[32:47], v[112:115], v[160:163], v[32:47]
	s_waitcnt lgkmcnt(4)
	v_mfma_f32_32x32x16_bf16 v[32:47], v[116:119], v[164:167], v[32:47]
	s_waitcnt lgkmcnt(2)
	v_mfma_f32_32x32x16_bf16 v[32:47], v[120:123], v[168:171], v[32:47]
	s_waitcnt lgkmcnt(0)
	v_mfma_f32_32x32x16_bf16 v[32:47], v[124:127], v[172:175], v[32:47]
	s_setprio 0
	v_sub_f32_e32 v160, v176, v227
	v_cmp_ge_f32_e32 vcc, s71, v160
	v_max_f32_e32 v160, v227, v227
	v_max_f32_e32 v160, v160, v176
	v_sub_f32_e32 v161, v227, v160
	v_mul_f32_e32 v161, 0x3e38aa3b, v161
	v_exp_f32_e32 v161, v161
	s_cmp_eq_u64 vcc, exec
	s_cselect_b64 vcc, -1, 0
	v_cndmask_b32_e32 v229, v160, v227, vcc
	v_cndmask_b32_e64 v228, v161, 1.0, vcc
	v_mul_f32_e32 v160, 0xbe38aa3b, v229
	v_fma_f32 v80, v80, v197, v160
	v_fma_f32 v81, v81, v197, v160
	v_fma_f32 v82, v82, v197, v160
	v_fma_f32 v83, v83, v197, v160
	v_fma_f32 v84, v84, v197, v160
	v_fma_f32 v85, v85, v197, v160
	v_fma_f32 v86, v86, v197, v160
	v_fma_f32 v87, v87, v197, v160
	v_fma_f32 v88, v88, v197, v160
	v_fma_f32 v89, v89, v197, v160
	v_fma_f32 v90, v90, v197, v160
	v_fma_f32 v91, v91, v197, v160
	v_fma_f32 v92, v92, v197, v160
	v_fma_f32 v93, v93, v197, v160
	v_fma_f32 v94, v94, v197, v160
	v_fma_f32 v95, v95, v197, v160
	v_fma_f32 v166, v64, v197, v160
	v_fma_f32 v167, v65, v197, v160
	v_fma_f32 v168, v66, v197, v160
	v_fma_f32 v169, v67, v197, v160
	v_fma_f32 v170, v68, v197, v160
	v_fma_f32 v171, v69, v197, v160
	v_fma_f32 v172, v70, v197, v160
	v_fma_f32 v173, v71, v197, v160
	v_fma_f32 v174, v72, v197, v160
	v_fma_f32 v175, v73, v197, v160
	v_fma_f32 v176, v74, v197, v160
	v_fma_f32 v177, v75, v197, v160
	v_fma_f32 v178, v76, v197, v160
	v_fma_f32 v179, v77, v197, v160
	v_fma_f32 v180, v78, v197, v160
	v_fma_f32 v181, v79, v197, v160
	ds_read_b64_tr_b16 v[64:65], v230 offset:0x400
	ds_read_b64_tr_b16 v[66:67], v230 offset:0xc00
	ds_read_b64_tr_b16 v[68:69], v230 offset:0x1400
	ds_read_b64_tr_b16 v[70:71], v230 offset:0x1c00
	ds_read_b64_tr_b16 v[72:73], v230 offset:0x2400
	ds_read_b64_tr_b16 v[74:75], v230 offset:0x2c00
	ds_read_b64_tr_b16 v[76:77], v230 offset:0x3400
	ds_read_b64_tr_b16 v[78:79], v230 offset:0x3c00
	s_setprio 1
	s_waitcnt lgkmcnt(6)
	v_mfma_f32_32x32x16_bf16 v[16:31], v[112:115], v[64:67], v[16:31]
	s_waitcnt lgkmcnt(4)
	v_mfma_f32_32x32x16_bf16 v[16:31], v[116:119], v[68:71], v[16:31]
	s_waitcnt lgkmcnt(2)
	v_mfma_f32_32x32x16_bf16 v[16:31], v[120:123], v[72:75], v[16:31]
	s_waitcnt lgkmcnt(0)
	v_mfma_f32_32x32x16_bf16 v[16:31], v[124:127], v[76:79], v[16:31]
	s_setprio 0
	ds_read_b64_tr_b16 v[64:65], v230 offset:0x600
	ds_read_b64_tr_b16 v[66:67], v230 offset:0xe00
	ds_read_b64_tr_b16 v[68:69], v230 offset:0x1600
	ds_read_b64_tr_b16 v[70:71], v230 offset:0x1e00
	ds_read_b64_tr_b16 v[72:73], v230 offset:0x2600
	ds_read_b64_tr_b16 v[74:75], v230 offset:0x2e00
	ds_read_b64_tr_b16 v[76:77], v230 offset:0x3600
	ds_read_b64_tr_b16 v[78:79], v230 offset:0x3e00
	s_setprio 0
	s_lshl_b32 s1, s36, 13
	v_lshl_add_u64 v[160:161], s[64:65], 0, v[154:155]
	s_add_i32 s1, s75, s1
	s_waitcnt vmcnt(0) lgkmcnt(0)
	s_barrier
	s_setprio 1
	v_mfma_f32_32x32x16_bf16 v[0:15], v[112:115], v[64:67], v[0:15]
	v_lshl_add_u64 v[232:233], v[160:161], 0, s[58:59]
	s_add_i32 m0, s1, 0xc000
	v_lshl_add_u64 v[162:163], s[64:65], 0, v[156:157]
	s_add_i32 s0, s75, s0
	global_load_lds_dwordx4 v[232:233], off
	v_mfma_f32_32x32x16_bf16 v[0:15], v[116:119], v[68:71], v[0:15]
	v_lshl_add_u64 v[232:233], v[162:163], 0, s[10:11]
	s_mov_b32 m0, s0
	v_lshl_add_u64 v[164:165], s[64:65], 0, v[158:159]
	global_load_lds_dwordx4 v[232:233], off
	v_mfma_f32_32x32x16_bf16 v[0:15], v[120:123], v[72:75], v[0:15]
	v_lshl_add_u64 v[232:233], v[164:165], 0, s[10:11]
	s_add_i32 m0, s0, 0x2000
	v_cmp_gt_f32_e32 vcc, 1.0, v228
	global_load_lds_dwordx4 v[232:233], off
	v_mfma_f32_32x32x16_bf16 v[0:15], v[124:127], v[76:79], v[0:15]
	s_setprio 0
	s_cbranch_vccz .LBB0_1054
	s_and_saveexec_b64 s[0:1], s[4:5]
	ds_write_b32 v223, v228 offset:128
	s_or_b64 exec, exec, s[0:1]
	s_waitcnt lgkmcnt(0)
	v_add_u32_e32 v76, s33, v188
	ds_read_b128 v[64:67], v76 offset:224
	ds_read_b128 v[68:71], v76 offset:192
	ds_read_b128 v[72:75], v76 offset:160
	ds_read_b128 v[76:79], v76 offset:128
	s_waitcnt lgkmcnt(0)
	v_pk_mul_f32 v[60:61], v[60:61], v[64:65]
	v_pk_mul_f32 v[56:57], v[56:57], v[68:69]
	v_pk_mul_f32 v[52:53], v[52:53], v[72:73]
	v_pk_mul_f32 v[62:63], v[62:63], v[66:67]
	v_pk_mul_f32 v[58:59], v[58:59], v[70:71]
	v_pk_mul_f32 v[54:55], v[54:55], v[74:75]
	v_pk_mul_f32 v[50:51], v[50:51], v[78:79]
	v_pk_mul_f32 v[48:49], v[48:49], v[76:77]
	v_pk_mul_f32 v[44:45], v[44:45], v[64:65]
	v_pk_mul_f32 v[40:41], v[40:41], v[68:69]
	v_pk_mul_f32 v[36:37], v[36:37], v[72:73]
	v_pk_mul_f32 v[46:47], v[46:47], v[66:67]
	v_pk_mul_f32 v[42:43], v[42:43], v[70:71]
	v_pk_mul_f32 v[38:39], v[38:39], v[74:75]
	v_pk_mul_f32 v[34:35], v[34:35], v[78:79]
	v_pk_mul_f32 v[32:33], v[32:33], v[76:77]
	v_pk_mul_f32 v[28:29], v[28:29], v[64:65]
	v_pk_mul_f32 v[24:25], v[24:25], v[68:69]
	v_pk_mul_f32 v[20:21], v[20:21], v[72:73]
	v_pk_mul_f32 v[30:31], v[30:31], v[66:67]
	v_pk_mul_f32 v[26:27], v[26:27], v[70:71]
	v_pk_mul_f32 v[22:23], v[22:23], v[74:75]
	v_pk_mul_f32 v[18:19], v[18:19], v[78:79]
	v_pk_mul_f32 v[16:17], v[16:17], v[76:77]
	v_pk_mul_f32 v[12:13], v[12:13], v[64:65]
	v_pk_mul_f32 v[8:9], v[8:9], v[68:69]
	v_pk_mul_f32 v[4:5], v[4:5], v[72:73]
	v_pk_mul_f32 v[14:15], v[14:15], v[66:67]
	v_pk_mul_f32 v[10:11], v[10:11], v[70:71]
	v_pk_mul_f32 v[6:7], v[6:7], v[74:75]
	v_pk_mul_f32 v[2:3], v[2:3], v[78:79]
	v_pk_mul_f32 v[0:1], v[0:1], v[76:77]
